# grid barriers: L1/L2 invalidate issued at arrival (overlapped with spin / top-level atomic) instead of after release
# speedup vs baseline: 1.0300x; 1.0099x over previous
.LBB0_30:
	s_or_b64 exec, exec, s[10:11]
	v_cvt_f32_u32_e32 v5, v3
	s_waitcnt vmcnt(0)
	v_readfirstlane_b32 s7, v4
	v_sub_u32_e32 v4, 0, v3
	v_rcp_iflag_f32_e32 v5, v5
	v_add_u32_e32 v6, s7, v2
	v_mul_f32_e32 v5, 0x4f7ffffe, v5
	v_cvt_u32_f32_e32 v5, v5
	v_mul_lo_u32 v2, v4, v5
	v_mul_hi_u32 v2, v5, v2
	v_add_u32_e32 v2, v5, v2
	v_mul_hi_u32 v2, v6, v2
	v_mul_lo_u32 v4, v2, v3
	v_sub_u32_e32 v4, v6, v4
	v_add_u32_e32 v5, 1, v2
	v_cmp_ge_u32_e32 vcc, v4, v3
	s_nop 1
	v_cndmask_b32_e32 v2, v2, v5, vcc
	v_sub_u32_e32 v5, v4, v3
	v_cndmask_b32_e32 v4, v4, v5, vcc
	v_add_u32_e32 v5, 1, v2
	v_cmp_ge_u32_e32 vcc, v4, v3
	v_add_u32_e32 v4, 1, v6
	s_nop 0
	v_cndmask_b32_e32 v2, v2, v5, vcc
	v_mul_lo_u32 v5, v3, v2
	v_add_u32_e32 v3, v5, v3
	v_cmp_ne_u32_e32 vcc, v4, v3
	s_and_saveexec_b64 s[8:9], vcc
	s_xor_b64 s[8:9], exec, s[8:9]
	s_cbranch_execz .LBB0_44
	s_waitcnt lgkmcnt(0)
	v_mov_b32_e32 v1, 0x2000
	buffer_inv sc1
	global_load_dword v1, v1, s[4:5] offset:1024 sc1
	s_add_u32 s14, s4, 0x2400
	s_addc_u32 s15, s5, 0
	s_waitcnt vmcnt(0)
	v_cmp_eq_u32_e32 vcc, v1, v2
	s_and_saveexec_b64 s[10:11], vcc
	s_cbranch_execz .LBB0_43
	s_add_u32 s12, s82, 0x4200
	s_addc_u32 s13, s83, 0
	s_mov_b32 s7, 1
	s_mov_b64 s[16:17], 0
	v_mov_b32_e32 v1, 0
	s_branch .LBB0_34

.LBB0_43:
	s_or_b64 exec, exec, s[10:11]
	s_waitcnt vmcnt(0)
	s_waitcnt vmcnt(0)

.LBB0_47:
	s_or_b64 exec, exec, s[10:11]
	buffer_inv sc1
	v_cvt_f32_u32_e32 v4, v1
	s_waitcnt vmcnt(0)
	v_readfirstlane_b32 s7, v3
	s_add_u32 s10, s82, 0x7500
	s_addc_u32 s11, s83, 0
	v_rcp_iflag_f32_e32 v4, v4
	v_add_u32_e32 v2, s7, v2
	v_add_u32_e32 v5, 1, v2
	s_mov_b64 s[12:13], -1
	v_mul_f32_e32 v3, 0x4f7ffffe, v4
	v_cvt_u32_f32_e32 v3, v3
	v_sub_u32_e32 v4, 0, v1
	v_mul_lo_u32 v4, v4, v3
	v_mul_hi_u32 v4, v3, v4
	v_add_u32_e32 v3, v3, v4
	v_mul_hi_u32 v3, v2, v3
	v_mul_lo_u32 v4, v3, v1
	v_sub_u32_e32 v2, v2, v4
	v_add_u32_e32 v6, 1, v3
	v_cmp_ge_u32_e32 vcc, v2, v1
	v_sub_u32_e32 v4, v2, v1
	s_nop 0
	v_cndmask_b32_e32 v3, v3, v6, vcc
	v_cndmask_b32_e32 v2, v2, v4, vcc
	v_add_u32_e32 v4, 1, v3
	v_cmp_ge_u32_e32 vcc, v2, v1
	s_nop 1
	v_cndmask_b32_e32 v4, v3, v4, vcc
	v_mul_lo_u32 v2, v1, v4
	v_add_u32_e32 v1, v2, v1
	v_cmp_ne_u32_e32 vcc, v5, v1
	v_mov_b64_e32 v[2:3], s[10:11]
	s_and_saveexec_b64 s[8:9], vcc
	s_cbranch_execz .LBB0_59
	v_mov_b32_e32 v1, 0
	global_load_dword v2, v1, s[10:11] sc1
	s_mov_b64 s[16:17], 0
	s_waitcnt vmcnt(0)
	v_cmp_eq_u32_e32 vcc, v2, v4
	s_and_saveexec_b64 s[14:15], vcc
	s_cbranch_execz .LBB0_58
	s_add_u32 s12, s82, 0x4200
	s_addc_u32 s13, s83, 0
	s_mov_b32 s7, 1
	s_branch .LBB0_51

.LBB0_61:
	s_or_b64 exec, exec, s[8:9]
	s_mov_b64 s[8:9], exec
	v_mbcnt_lo_u32_b32 v1, s8, 0
	v_mbcnt_hi_u32_b32 v1, s9, v1
	v_cmp_eq_u32_e32 vcc, 0, v1
	s_waitcnt vmcnt(0)
	s_and_saveexec_b64 s[10:11], vcc
	s_cbranch_execz .LBB0_63
	s_bcnt1_i32_b64 s7, s[8:9]
	v_mov_b32_e32 v1, 0x2000
	v_mov_b32_e32 v2, s7
	global_atomic_add v1, v2, s[4:5] offset:1024

.LBB0_137:
	s_or_b64 exec, exec, s[6:7]
	v_cvt_f32_u32_e32 v6, v4
	s_waitcnt vmcnt(0)
	v_readfirstlane_b32 s4, v5
	v_sub_u32_e32 v5, 0, v4
	v_rcp_iflag_f32_e32 v6, v6
	v_add_u32_e32 v7, s4, v3
	v_mul_f32_e32 v6, 0x4f7ffffe, v6
	v_cvt_u32_f32_e32 v6, v6
	v_mul_lo_u32 v3, v5, v6
	v_mul_hi_u32 v3, v6, v3
	v_add_u32_e32 v3, v6, v3
	v_mul_hi_u32 v3, v7, v3
	v_mul_lo_u32 v5, v3, v4
	v_sub_u32_e32 v5, v7, v5
	v_add_u32_e32 v6, 1, v3
	v_cmp_ge_u32_e32 vcc, v5, v4
	s_nop 1
	v_cndmask_b32_e32 v3, v3, v6, vcc
	v_sub_u32_e32 v6, v5, v4
	v_cndmask_b32_e32 v5, v5, v6, vcc
	v_add_u32_e32 v6, 1, v3
	v_cmp_ge_u32_e32 vcc, v5, v4
	v_add_u32_e32 v5, 1, v7
	s_nop 0
	v_cndmask_b32_e32 v3, v3, v6, vcc
	v_mul_lo_u32 v6, v4, v3
	v_add_u32_e32 v4, v6, v4
	v_cmp_ne_u32_e32 vcc, v5, v4
	s_and_saveexec_b64 s[4:5], vcc
	s_xor_b64 s[4:5], exec, s[4:5]
	s_cbranch_execz .LBB0_151
	s_waitcnt lgkmcnt(0)
	v_mov_b32_e32 v2, 0x2000
	buffer_inv sc1
	global_load_dword v2, v2, s[2:3] offset:1024 sc1
	s_add_u32 s10, s2, 0x2400
	s_addc_u32 s11, s3, 0
	s_waitcnt vmcnt(0)
	v_cmp_eq_u32_e32 vcc, v2, v3
	s_and_saveexec_b64 s[6:7], vcc
	s_cbranch_execz .LBB0_150
	s_add_u32 s8, s82, 0x4200
	s_addc_u32 s9, s83, 0
	s_mov_b32 s22, 1
	s_mov_b64 s[12:13], 0
	v_mov_b32_e32 v2, 0
	s_branch .LBB0_141

.LBB0_150:
	s_or_b64 exec, exec, s[6:7]
	s_waitcnt vmcnt(0)
	s_waitcnt vmcnt(0)

.LBB0_154:
	s_or_b64 exec, exec, s[6:7]
	buffer_inv sc1
	v_cvt_f32_u32_e32 v5, v2
	s_waitcnt vmcnt(0)
	v_readfirstlane_b32 s4, v4
	s_add_u32 s6, s82, 0x7500
	s_addc_u32 s7, s83, 0
	v_rcp_iflag_f32_e32 v5, v5
	v_add_u32_e32 v3, s4, v3
	v_add_u32_e32 v6, 1, v3
	s_mov_b64 s[8:9], -1
	v_mul_f32_e32 v4, 0x4f7ffffe, v5
	v_cvt_u32_f32_e32 v4, v4
	v_sub_u32_e32 v5, 0, v2
	v_mul_lo_u32 v5, v5, v4
	v_mul_hi_u32 v5, v4, v5
	v_add_u32_e32 v4, v4, v5
	v_mul_hi_u32 v4, v3, v4
	v_mul_lo_u32 v5, v4, v2
	v_sub_u32_e32 v3, v3, v5
	v_add_u32_e32 v7, 1, v4
	v_cmp_ge_u32_e32 vcc, v3, v2
	v_sub_u32_e32 v5, v3, v2
	s_nop 0
	v_cndmask_b32_e32 v4, v4, v7, vcc
	v_cndmask_b32_e32 v3, v3, v5, vcc
	v_add_u32_e32 v5, 1, v4
	v_cmp_ge_u32_e32 vcc, v3, v2
	s_nop 1
	v_cndmask_b32_e32 v4, v4, v5, vcc
	v_mul_lo_u32 v3, v2, v4
	v_add_u32_e32 v2, v3, v2
	v_cmp_ne_u32_e32 vcc, v6, v2
	v_mov_b64_e32 v[2:3], s[6:7]
	s_and_saveexec_b64 s[4:5], vcc
	s_cbranch_execz .LBB0_166
	v_mov_b32_e32 v2, 0
	global_load_dword v3, v2, s[6:7] sc1
	s_mov_b64 s[12:13], 0
	s_waitcnt vmcnt(0)
	v_cmp_eq_u32_e32 vcc, v3, v4
	s_and_saveexec_b64 s[10:11], vcc
	s_cbranch_execz .LBB0_165
	s_add_u32 s8, s82, 0x4200
	s_addc_u32 s9, s83, 0
	s_mov_b32 s22, 1
	s_branch .LBB0_158

.LBB0_168:
	s_or_b64 exec, exec, s[4:5]
	s_mov_b64 s[4:5], exec
	v_mbcnt_lo_u32_b32 v2, s4, 0
	v_mbcnt_hi_u32_b32 v2, s5, v2
	v_cmp_eq_u32_e32 vcc, 0, v2
	s_waitcnt vmcnt(0)
	s_and_saveexec_b64 s[6:7], vcc
	s_cbranch_execz .LBB0_170
	s_bcnt1_i32_b64 s4, s[4:5]
	v_mov_b32_e32 v2, 0x2000
	v_mov_b32_e32 v3, s4
	global_atomic_add v2, v3, s[2:3] offset:1024
